# v21 + FFN weight-copy work re-balanced between idle slots: XQF_N 9856->14336, L1FILL_NA 10240->16384 with the attention phase's deferred stream started 6144 items later
# speedup vs baseline: 1.0074x; 1.0034x over previous
.LBB0_16:
	v_writelane_b32 v251, s95, 48
	s_andn2_b64 vcc, exec, s[0:1]
	v_writelane_b32 v251, s97, 49
	s_cbranch_vccnz .LBB0_538
	v_readlane_b32 s2, v251, 2
	v_readlane_b32 s3, v251, 3
	v_mov_b32 v1, 0
	s_and_b32 s85, s54, 0xffffffc0
	v_mbcnt_lo_u32_b32 v1, -1, v1
	v_mbcnt_hi_u32_b32 v2, -1, v1
	s_lshl_b32 s27, s95, 3
	s_lshl_b32 s4, s97, 3
	v_add_u32_e32 v3, s85, v2
	s_cmpk_eq_i32 s97, 0x100
	v_readfirstlane_b32 s29, v3
	s_cselect_b32 s11, 0x3800, 0
	s_ashr_i32 s28, s29, 6
	s_mul_i32 s0, s28, 0x2100
	s_sub_i32 s5, 0x5600, s11
	s_lshl_b32 s96, s97, 9
	v_and_b32_e32 v1, 63, v2
	s_add_i32 s10, s0, 0
	s_add_i32 s26, s28, s27
	s_movk_i32 s13, 0x5600
	s_cmp_ge_i32 s26, s5
	v_lshrrev_b32_e32 v77, 4, v1
	v_lshlrev_b32_e32 v78, 2, v1
	v_and_b32_e32 v76, 7, v2
	v_lshrrev_b32_e32 v88, 3, v1
	s_mov_b32 s12, s26
	s_cbranch_scc1 .LBB0_84
	v_readlane_b32 s36, v251, 16
	v_mov_b32_e32 v2, 0
	v_readlane_b32 s44, v251, 24
	v_readlane_b32 s45, v251, 25
	v_lshlrev_b32_e32 v4, 4, v76
	v_mov_b32_e32 v5, v2
	s_cmp_lg_u64 s[44:45], 0
	v_lshl_add_u64 v[4:5], s[2:3], 0, v[4:5]
	s_mov_b64 s[0:1], 0x8c00000
	s_cselect_b64 s[6:7], -1, 0
	v_and_b32_e32 v79, 60, v78
	v_lshrrev_b32_e32 v81, 3, v1
	v_lshl_add_u64 v[70:71], v[4:5], 0, s[0:1]
	s_add_i32 s0, s11, s28
	v_lshl_add_u32 v3, v79, 2, s10
	v_mul_u32_u24_e32 v6, 0x104, v77
	v_mul_u32_u24_e32 v7, 0x410, v76
	v_lshlrev_b32_e32 v4, 2, v81
	s_add_i32 s0, s0, s27
	v_lshlrev_b32_e32 v80, 1, v77
	v_add3_u32 v82, s10, v7, v4
	v_or_b32_e32 v83, 8, v81
	v_or_b32_e32 v84, 16, v81
	v_or_b32_e32 v85, 24, v81
	v_or_b32_e32 v86, 32, v81
	v_or_b32_e32 v87, 40, v81
	v_or_b32_e32 v89, 48, v81
	v_or_b32_e32 v90, 56, v81
	s_lshl_b32 s14, s0, 6
	s_mov_b32 s15, 0x15800
	v_add_u32_e32 v91, v3, v6
	s_mov_b32 s12, s26
	v_readlane_b32 s37, v251, 17
	v_readlane_b32 s38, v251, 18
	v_readlane_b32 s39, v251, 19
	v_readlane_b32 s40, v251, 20
	v_readlane_b32 s41, v251, 21
	v_readlane_b32 s42, v251, 22
	v_readlane_b32 s43, v251, 23
	v_readlane_b32 s46, v251, 26
	v_readlane_b32 s47, v251, 27
	v_readlane_b32 s48, v251, 28
	v_readlane_b32 s49, v251, 29
	v_readlane_b32 s50, v251, 30
	v_readlane_b32 s51, v251, 31
	s_branch .LBB0_20

.LBB0_680:
	s_lshr_b32 s11, s54, 6
	s_cmpk_lt_i32 s95, 0x700
	s_cselect_b64 s[0:1], -1, 0
	v_writelane_b32 v252, s0, 9
	s_ashr_i32 s81, s95, 31
	s_ashr_i32 s14, s97, 31
	v_writelane_b32 v252, s1, 10
	s_lshr_b32 s0, s81, 29
	s_add_i32 s12, s95, s0
	s_and_b32 s1, s12, -8
	s_ashr_i32 s0, s12, 3
	s_sub_i32 s1, s95, s1
	v_readlane_b32 s16, v251, 2
	v_readlane_b32 s17, v251, 3
	s_add_u32 s2, s16, 0x4200
	s_addc_u32 s3, s17, 0
	v_writelane_b32 v251, s2, 63
	s_lshl_b32 s87, s55, 8
	v_readlane_b32 s36, v251, 16
	v_writelane_b32 v252, s3, 0
	s_add_u32 s2, s56, s87
	s_addc_u32 s3, s57, 0
	s_add_u32 s4, s2, 0x1400
	s_addc_u32 s5, s3, 0
	v_writelane_b32 v252, s4, 11
	s_add_u32 s2, s2, 0x2400
	s_addc_u32 s3, s3, 0
	v_writelane_b32 v252, s5, 12
	v_writelane_b32 v252, s2, 13
	v_readlane_b32 s44, v251, 24
	v_readlane_b32 s45, v251, 25
	v_writelane_b32 v252, s3, 14
	s_add_u32 s2, s16, 0x7400
	s_addc_u32 s3, s17, 0
	v_writelane_b32 v252, s2, 15
	s_mov_b32 s77, 0
	v_readlane_b32 s42, v251, 22
	v_writelane_b32 v252, s3, 16
	s_add_u32 s2, s16, 0x7500
	s_addc_u32 s3, s17, 0
	v_writelane_b32 v252, s2, 17
	s_cmp_lt_i32 s95, 64
	v_readlane_b32 s43, v251, 23
	v_writelane_b32 v252, s3, 18
	s_cselect_b64 s[2:3], -1, 0
	s_lshl_b32 s9, s1, 3
	v_writelane_b32 v252, s2, 19
	s_cmp_gt_i32 s95, 63
	v_readlane_b32 s50, v251, 30
	v_writelane_b32 v252, s3, 20
	s_cselect_b64 s[2:3], -1, 0
	v_writelane_b32 v252, s2, 21
	v_readlane_b32 s51, v251, 31
	v_readlane_b32 s18, v251, 50
	v_writelane_b32 v252, s3, 22
	s_sub_i32 s2, s95, 64
	s_cmp_lt_u32 s2, 64
	v_writelane_b32 v252, s2, 23
	s_cselect_b64 s[2:3], -1, 0
	s_lshl_b32 s19, s95, 3
	s_and_b32 s7, s19, 56
	s_bfe_u32 s8, s95, 0x30003
	v_writelane_b32 v252, s2, 24
	s_cmpk_eq_i32 s97, 0x100
	v_readlane_b32 s37, v251, 17
	v_writelane_b32 v252, s3, 25
	s_cselect_b64 s[2:3], -1, 0
	s_and_b64 s[4:5], s[2:3], exec
	s_cselect_b32 s6, 0x80, 0
	s_sub_i32 s4, s97, s6
	s_cmp_ge_i32 s95, s6
	s_cselect_b64 s[20:21], -1, 0
	v_writelane_b32 v252, s20, 26
	s_mul_i32 s5, s11, 0x2100
	s_add_i32 s5, s5, 0
	v_writelane_b32 v252, s21, 27
	v_writelane_b32 v252, s5, 28
	s_sub_i32 s5, s95, s6
	s_lshl_b32 s5, s5, 3
	s_add_i32 s28, s5, s11
	s_cmpk_lt_i32 s28, 0x4000
	s_cselect_b64 s[20:21], -1, 0
	v_writelane_b32 v252, s20, 29
	v_readlane_b32 s38, v251, 18
	v_readlane_b32 s39, v251, 19
	v_writelane_b32 v252, s21, 30
	v_readlane_b32 s20, v251, 8
	v_readlane_b32 s22, v251, 10
	v_readlane_b32 s23, v251, 11
	s_add_u32 s22, s22, 0x15800000
	s_addc_u32 s23, s23, 0
	s_add_u32 s70, s44, 0x8000
	v_writelane_b32 v252, s22, 5
	s_addc_u32 s71, s45, 0
	s_lshl_b32 s4, s4, 3
	v_writelane_b32 v252, s23, 6
	s_cmp_lt_i32 s95, 32
	v_writelane_b32 v252, s4, 31
	s_cselect_b64 s[4:5], -1, 0
	v_writelane_b32 v252, s4, 32
	s_lshl_b32 s10, s1, 2
	v_readlane_b32 s21, v251, 9
	v_writelane_b32 v252, s5, 33
	s_add_u32 s4, s16, 0x1000
	s_addc_u32 s5, s17, 0
	v_writelane_b32 v252, s4, 34
	s_cmpk_lt_i32 s95, 0x800
	v_readlane_b32 s24, v251, 12
	v_writelane_b32 v252, s5, 35
	s_cselect_b64 s[4:5], -1, 0
	v_writelane_b32 v252, s4, 36
	s_and_b32 s13, s1, 3
	s_add_i32 s76, s1, 32
	v_writelane_b32 v252, s5, 37
	s_lshl_b32 s5, s12, 2
	s_and_b32 s12, s5, 0xffffffe0
	s_ashr_i32 s4, s1, 2
	s_sub_i32 s15, 0x1fe0, s12
	s_ashr_i32 s5, s4, 31
	v_writelane_b32 v252, s15, 38
	s_ashr_i32 s15, s15, 31
	v_writelane_b32 v252, s15, 39
	s_lshl_b64 s[4:5], s[4:5], 26
	v_writelane_b32 v252, s4, 40
	s_add_i32 s22, s11, s19
	v_readlane_b32 s25, v251, 13
	v_writelane_b32 v252, s5, 41
	s_lshl_b32 s4, s13, 10
	v_writelane_b32 v252, s4, 42
	s_lshl_b64 s[4:5], s[76:77], 21
	v_writelane_b32 v252, s4, 43
	v_readlane_b32 s26, v251, 14
	v_readlane_b32 s27, v251, 15
	v_writelane_b32 v252, s5, 44
	s_sub_i32 s4, 0x1de1, s12
	s_max_i32 s4, s4, 0
	s_and_b32 s76, s4, 0x7fffffc0
	s_lshl_b64 s[4:5], s[76:77], 8
	v_writelane_b32 v252, s4, 45
	v_readlane_b32 s40, v251, 20
	v_readlane_b32 s41, v251, 21
	v_writelane_b32 v252, s5, 46
	s_add_u32 s4, s20, 0x800000
	s_addc_u32 s5, s21, 0
	v_writelane_b32 v252, s4, 47
	v_readlane_b32 s46, v251, 26
	v_readlane_b32 s47, v251, 27
	v_writelane_b32 v252, s5, 48
	s_mov_b64 s[4:5], s[52:53]
	v_readlane_b32 s52, v251, 32
	v_readlane_b32 s64, v251, 44
	v_readlane_b32 s65, v251, 45
	s_mov_b64 s[24:25], s[64:65]
	s_mov_b64 s[64:65], s[4:5]
	s_add_u32 s4, s24, 0x800000
	s_addc_u32 s5, s25, 0
	v_writelane_b32 v252, s4, 49
	v_readlane_b32 s67, v251, 47
	s_mov_b32 s67, s14
	v_writelane_b32 v252, s5, 50
	s_add_u32 s4, s42, 0x8000
	s_addc_u32 s5, s43, 0
	s_lshl_b32 s90, s97, 3
	v_writelane_b32 v252, s4, 51
	s_cmpk_lt_i32 s95, 0x400
	v_readlane_b32 s56, v251, 36
	v_writelane_b32 v252, s5, 52
	s_cselect_b64 s[4:5], -1, 0
	v_writelane_b32 v252, s4, 53
	v_readlane_b32 s57, v251, 37
	v_readlane_b32 s58, v251, 38
	v_writelane_b32 v252, s5, 54
	s_ashr_i32 s4, s95, 4
	s_lshl_b32 s5, s95, 1
	s_and_b32 s4, s4, -16
	s_and_b32 s5, s5, 12
	s_or_b32 s4, s4, s5
	s_bfe_u32 s5, s95, 0x20006
	s_or_b32 s20, s4, s5
	s_and_b32 s4, s19, 8
	s_or_b32 s23, s4, s8
	s_mov_b64 s[4:5], 0
	v_writelane_b32 v252, s4, 55
	s_cmp_lg_u64 s[50:51], 0
	v_readlane_b32 s59, v251, 39
	v_writelane_b32 v252, s5, 56
	s_cselect_b64 s[4:5], -1, 0
	v_writelane_b32 v252, s4, 57
	s_cmp_gt_i32 s65, 3
	v_readlane_b32 s48, v251, 28
	v_writelane_b32 v252, s5, 58
	s_cselect_b64 s[4:5], -1, 0
	v_writelane_b32 v252, s4, 59
	s_cmpk_gt_i32 s97, 0xff
	v_readlane_b32 s49, v251, 29
	v_writelane_b32 v252, s5, 60
	s_cselect_b64 s[4:5], -1, 0
	v_writelane_b32 v252, s4, 61
	s_cmpk_lt_i32 s95, 0x80
	v_readlane_b32 s53, v251, 33
	v_writelane_b32 v252, s5, 62
	s_cselect_b64 s[4:5], -1, 0
	s_lshl_b32 s14, s1, 4
	v_writelane_b32 v252, s4, 63
	s_cmpk_lt_u32 s95, 0x100
	v_readlane_b32 s54, v251, 34
	v_writelane_b32 v253, s5, 0
	s_cselect_b64 s[4:5], -1, 0
	v_writelane_b32 v253, s4, 1
	s_lshr_b32 s11, s95, 5
	s_or_b32 s12, s7, s11
	v_writelane_b32 v253, s5, 2
	s_bfe_u32 s4, s95, 0x10003
	s_lshl_b32 s13, s12, 21
	s_lshl_b32 s25, s4, 20
	s_lshl_b32 s12, s12, 8
	s_lshl_b32 s4, s4, 7
	s_bfe_u32 s5, s95, 0x10004
	v_writelane_b32 v253, s13, 3
	s_or_b32 s4, s12, s4
	s_lshl_b32 s24, s5, 21
	v_writelane_b32 v253, s4, 4
	s_lshl_b32 s4, s5, 8
	s_cmpk_gt_i32 s95, 0x7f
	v_writelane_b32 v253, s4, 5
	s_cselect_b64 s[4:5], -1, 0
	v_writelane_b32 v253, s4, 6
	v_readlane_b32 s55, v251, 35
	v_readlane_b32 s60, v251, 40
	v_writelane_b32 v253, s5, 7
	s_add_i32 s5, s95, 0xffffff80
	s_cmp_lt_u32 s5, 16
	s_cselect_b64 s[12:13], -1, 0
	s_add_i32 s4, s95, 0x78
	v_writelane_b32 v253, s12, 8
	s_cmp_lt_u32 s5, 8
	v_readlane_b32 s61, v251, 41
	v_writelane_b32 v253, s13, 9
	s_cselect_b32 s12, s95, s4
	s_cmp_gt_u32 s5, 7
	v_writelane_b32 v253, s5, 10
	s_cselect_b64 s[4:5], -1, 0
	s_and_b32 s15, s12, 0x7f
	s_and_b64 s[12:13], s[4:5], exec
	s_cselect_b32 s12, 0x200000, 0
	v_writelane_b32 v253, s12, 11
	v_writelane_b32 v253, s15, 12
	s_lshl_b32 s12, s15, 21
	v_writelane_b32 v253, s12, 13
	s_add_i32 s12, s18, 0xfffec000
	s_cmpk_gt_i32 s95, 0x8f
	v_writelane_b32 v253, s12, 14
	s_cselect_b64 s[12:13], -1, 0
	s_and_b64 s[2:3], s[12:13], s[2:3]
	v_writelane_b32 v253, s2, 15
	v_cndmask_b32_e64 v226, 0, 1, s[4:5]
	s_movk_i32 s4, 0xe1
	v_writelane_b32 v253, s3, 16
	s_add_i32 s2, s22, 0xfffffb80
	s_cmpk_lt_i32 s2, 0x3800
	s_cselect_b64 s[2:3], -1, 0
	v_writelane_b32 v253, s2, 17
	s_cmp_lg_u64 s[44:45], 0
	s_mul_i32 s12, s1, 17
	v_writelane_b32 v253, s3, 18
	s_cselect_b64 s[2:3], -1, 0
	v_writelane_b32 v253, s2, 19
	s_cmpk_lt_i32 s95, 0x100
	v_readlane_b32 s62, v251, 42
	v_writelane_b32 v253, s3, 20
	s_cselect_b64 s[2:3], -1, 0
	v_writelane_b32 v253, s2, 21
	s_cmpk_lt_i32 s95, 0x1580
	v_readlane_b32 s63, v251, 43
	v_writelane_b32 v253, s3, 22
	s_cselect_b64 s[2:3], -1, 0
	v_writelane_b32 v253, s2, 23
	s_cmpk_lt_i32 s28, 0x2b00
	v_readlane_b32 s66, v251, 46
	v_writelane_b32 v253, s3, 24
	s_cselect_b64 s[2:3], -1, 0
	v_writelane_b32 v253, s2, 25
	s_cmp_lt_i32 s1, 0
	s_cselect_b32 s4, s4, 0xe0
	v_writelane_b32 v253, s3, 26
	v_cmp_eq_u32_e64 s[2:3], 0, v0
	s_mul_i32 s4, s1, s4
	v_mov_b32_e32 v145, 0
	v_writelane_b32 v253, s2, 27
	s_mov_b64 s[88:89], 0x80
	s_movk_i32 s60, 0xf000
	v_writelane_b32 v253, s3, 28
	s_mul_i32 s2, s1, 9
	s_mul_i32 s3, s1, 5
	s_cselect_b32 s5, s2, s9
	s_movk_i32 s2, 0x2b1
	s_cselect_b32 s3, s3, s10
	s_cselect_b32 s9, s12, s14
	s_cselect_b32 s14, s2, 0x2b0
	s_add_i32 s4, s4, s0
	s_mul_hi_i32 s2, s4, 0x92492493
	s_add_i32 s2, s2, s4
	s_lshr_b32 s10, s2, 31
	s_ashr_i32 s2, s2, 7
	s_add_i32 s2, s2, s10
	s_mul_i32 s10, s2, 0xe0
	s_sub_i32 s4, s4, s10
	s_lshl_b32 s12, s2, 3
	s_bfe_u32 s2, s4, 0x3001c
	s_add_i32 s10, s4, s2
	s_sext_i32_i16 s13, s10
	s_and_b32 s10, s10, 0xfff8
	s_sub_i32 s4, s4, s10
	s_sext_i32_i16 s4, s4
	s_add_i32 s26, s12, s4
	s_ashr_i32 s4, s13, 3
	v_writelane_b32 v253, s4, 29
	s_add_i32 s4, s5, s0
	s_ashr_i32 s5, s4, 31
	s_lshr_b32 s5, s5, 27
	s_add_i32 s5, s4, s5
	s_ashr_i32 s10, s5, 5
	s_and_b32 s5, s5, 0xffe0
	s_sub_i32 s5, s4, s5
	s_bfe_i32 s4, s5, 0x80000
	s_lshr_b32 s12, s4, 7
	s_bfe_u32 s4, s12, 0x30005
	s_lshr_b32 s2, s13, 3
	s_add_i32 s13, s5, s4
	s_bfe_i32 s4, s13, 0x80000
	s_and_b32 s13, s13, 0xf8
	s_sub_i32 s13, s5, s13
	s_lshl_b32 s10, s10, 3
	s_sext_i32_i16 s15, s4
	s_sext_i32_i8 s13, s13
	s_add_i32 s30, s10, s13
	s_ashr_i32 s10, s15, 3
	v_writelane_b32 v253, s10, 30
	s_bfe_u32 s10, s12, 0x40004
	s_add_i32 s5, s5, s10
	s_bfe_i32 s5, s5, 0x80000
	s_sext_i32_i16 s5, s5
	s_lshr_b32 s10, s5, 4
	s_bfe_i64 s[12:13], s[10:11], 0x100000
	s_mov_b32 s10, s30
	s_ashr_i32 s31, s30, 31
	v_writelane_b32 v253, s10, 31
	s_lshr_b32 s4, s15, 3
	s_lshl_b64 s[30:31], s[30:31], 20
	v_writelane_b32 v253, s11, 32
	v_writelane_b32 v253, s30, 33
	s_bfe_i64 s[4:5], s[4:5], 0x100000
	s_lshl_b64 s[4:5], s[4:5], 21
	v_writelane_b32 v253, s31, 34
	v_writelane_b32 v253, s4, 35
	s_add_i32 s3, s3, s0
	s_ashr_i32 s21, s20, 31
	v_writelane_b32 v253, s5, 36
	s_lshl_b64 s[4:5], s[12:13], 24
	v_writelane_b32 v253, s4, 37
	s_mul_i32 s1, s1, s14
	s_add_i32 s1, s1, s0
	v_writelane_b32 v253, s5, 38
	s_or_b32 s4, s7, s8
	v_writelane_b32 v253, s4, 39
	s_lshl_b32 s4, s4, 21
	v_writelane_b32 v253, s4, 40
	s_ashr_i32 s4, s3, 31
	s_lshr_b32 s4, s4, 28
	s_add_i32 s4, s3, s4
	s_ashr_i32 s5, s4, 4
	s_and_b32 s4, s4, 0xfff0
	s_sub_i32 s3, s3, s4
	s_bfe_i32 s4, s3, 0x80000
	s_bfe_u32 s4, s4, 0x3000c
	s_add_i32 s7, s3, s4
	s_bfe_i32 s4, s7, 0x80000
	s_and_b32 s7, s7, 0xf8
	s_sub_i32 s3, s3, s7
	s_lshl_b32 s5, s5, 3
	s_sext_i32_i16 s8, s4
	s_sext_i32_i8 s3, s3
	s_add_i32 s12, s5, s3
	s_ashr_i32 s3, s8, 3
	s_lshr_b32 s4, s8, 3
	v_writelane_b32 v253, s3, 41
	s_mov_b32 s8, s12
	s_ashr_i32 s13, s12, 31
	v_writelane_b32 v253, s8, 42
	s_lshl_b64 s[12:13], s[12:13], 18
	s_bfe_i64 s[4:5], s[4:5], 0x100000
	v_writelane_b32 v253, s9, 43
	v_writelane_b32 v253, s12, 44
	s_lshl_b32 s3, s23, 21
	s_ashr_i32 s27, s26, 31
	v_writelane_b32 v253, s13, 45
	s_lshl_b64 s[12:13], s[4:5], 18
	v_writelane_b32 v253, s12, 46
	s_lshl_b64 s[4:5], s[4:5], 22
	v_mov_b32_e32 v227, 1
	v_writelane_b32 v253, s13, 47
	v_writelane_b32 v253, s4, 48
	s_movk_i32 s86, 0x70
	s_movk_i32 s82, 0xfdff
	v_writelane_b32 v253, s5, 49
	s_lshl_b64 s[4:5], s[20:21], 21
	v_writelane_b32 v253, s4, 50
	s_mov_b32 s78, 0x3e0293ee
	s_mov_b32 s83, 0x41380000
	v_writelane_b32 v253, s5, 51
	v_writelane_b32 v253, s3, 52
	s_lshl_b32 s3, s23, 9
	s_and_b32 s3, s3, 0x1800
	v_writelane_b32 v253, s3, 53
	s_lshl_b32 s3, s23, 19
	v_writelane_b32 v253, s3, 54
	s_add_i32 s3, s9, s0
	s_ashr_i32 s4, s3, 31
	s_lshr_b32 s4, s4, 28
	s_add_i32 s4, s3, s4
	s_ashr_i32 s5, s4, 4
	s_and_b32 s4, s4, 0xfff0
	s_sub_i32 s3, s3, s4
	s_bfe_i32 s4, s3, 0x80000
	s_bfe_u32 s4, s4, 0x3000c
	s_add_i32 s7, s3, s4
	s_bfe_i32 s4, s7, 0x80000
	s_and_b32 s7, s7, 0xf8
	s_sub_i32 s3, s3, s7
	s_lshl_b32 s5, s5, 3
	s_sext_i32_i16 s8, s4
	s_sext_i32_i8 s3, s3
	s_add_i32 s12, s5, s3
	s_ashr_i32 s3, s8, 3
	s_lshr_b32 s4, s8, 3
	v_writelane_b32 v253, s3, 55
	s_mov_b32 s8, s12
	s_ashr_i32 s13, s12, 31
	v_writelane_b32 v253, s8, 56
	s_bfe_i64 s[4:5], s[4:5], 0x100000
	s_lshl_b64 s[4:5], s[4:5], 21
	v_writelane_b32 v253, s9, 57
	s_lshl_b64 s[8:9], s[12:13], 21
	v_writelane_b32 v253, s8, 58
	s_lshl_b32 s3, s23, 18
	s_mul_hi_i32 s0, s1, 0x2fa0be83
	v_writelane_b32 v253, s9, 59
	v_writelane_b32 v253, s4, 60
	s_movk_i32 s61, 0xe000
	s_brev_b32 s63, -2
	v_writelane_b32 v253, s5, 61
	s_mov_b32 s4, s20
	v_writelane_b32 v253, s4, 62
	s_brev_b32 s68, 1
	v_mov_b32_e32 v228, 0x358637bd
	v_writelane_b32 v253, s5, 63
	s_lshl_b64 s[4:5], s[20:21], 18
	v_writelane_b32 v254, s4, 0
	s_mov_b32 s38, 0xf800000
	v_mov_b32_e32 v229, 0x260
	v_writelane_b32 v254, s5, 1
	v_writelane_b32 v254, s23, 2
	v_writelane_b32 v254, s3, 3
	s_lshr_b32 s3, s0, 31
	s_ashr_i32 s0, s0, 7
	s_add_i32 s0, s0, s3
	s_lshl_b32 s3, s0, 3
	s_mulk_i32 s0, 0x2b0
	s_sub_i32 s1, s1, s0
	s_bfe_u32 s0, s1, 0x3001c
	s_add_i32 s4, s1, s0
	s_sext_i32_i16 s5, s4
	s_and_b32 s4, s4, 0xfff8
	s_sub_i32 s1, s1, s4
	s_sext_i32_i16 s1, s1
	s_add_i32 s8, s3, s1
	s_ashr_i32 s1, s5, 3
	v_writelane_b32 v254, s1, 4
	s_mov_b32 s4, s26
	s_lshr_b32 s0, s5, 3
	v_writelane_b32 v254, s4, 5
	s_bfe_i64 s[2:3], s[2:3], 0x100000
	s_lshl_b64 s[2:3], s[2:3], 21
	v_writelane_b32 v254, s5, 6
	s_lshl_b64 s[4:5], s[26:27], 21
	v_writelane_b32 v254, s4, 7
	s_ashr_i32 s9, s8, 31
	s_bfe_i64 s[0:1], s[0:1], 0x100000
	v_writelane_b32 v254, s5, 8
	v_writelane_b32 v254, s2, 9
	s_lshl_b64 s[0:1], s[0:1], 21
	s_mov_b64 s[4:5], -1
	v_writelane_b32 v254, s3, 10
	s_mov_b32 s2, s8
	v_writelane_b32 v254, s2, 11
	s_mov_b32 s39, 0xf7fff000
	s_brev_b32 s40, 31
	v_writelane_b32 v254, s3, 12
	s_lshl_b64 s[2:3], s[8:9], 21
	v_writelane_b32 v254, s2, 13
	s_add_u32 s74, s16, 0x4400
	s_addc_u32 s75, s17, 0
	v_writelane_b32 v254, s3, 14
	v_writelane_b32 v254, s0, 15
	s_ashr_i32 s91, s90, 31
	s_lshl_b64 s[56:57], s[90:91], 13
	v_writelane_b32 v254, s1, 16
	v_writelane_b32 v254, s28, 17
	s_lshl_b32 s0, s28, 6
	v_writelane_b32 v254, s0, 18
	s_lshl_b32 s1, s97, 9
	s_lshl_b32 s0, s6, 9
	s_sub_i32 s0, s1, s0
	v_writelane_b32 v254, s0, 19
	v_writelane_b32 v254, s19, 20
	s_ashr_i32 s0, s19, 31
	v_writelane_b32 v252, s1, 3
	v_writelane_b32 v254, s0, 21
	s_lshl_b64 s[0:1], s[90:91], 2
	v_writelane_b32 v252, s0, 1
	s_lshl_b64 s[58:59], s[90:91], 8
	s_movk_i32 s41, 0xd000
	v_writelane_b32 v252, s1, 2
	s_add_u32 s0, s36, 0x3810
	v_writelane_b32 v254, s0, 22
	s_addc_u32 s0, s37, 0
	v_writelane_b32 v254, s0, 23
	s_lshl_b64 s[0:1], s[90:91], 14
	v_writelane_b32 v254, s0, 24
	v_writelane_b32 v252, s56, 7
	v_mov_b32_e32 v230, 0xff800000
	v_writelane_b32 v254, s1, 25
	v_writelane_b32 v254, s24, 26
	s_or_b32 s0, s24, 0x7000100
	v_writelane_b32 v254, s0, 27
	s_and_b32 s0, s95, 7
	s_lshl_b32 s0, s0, 24
	s_lshl_b32 s1, s11, 21
	s_add_i32 s0, s0, s1
	v_writelane_b32 v254, s25, 28
	s_or_b32 s0, s25, s0
	v_writelane_b32 v254, s0, 29
	s_add_u32 s0, s0, 0x29000080
	v_writelane_b32 v254, s0, 30
	s_addc_u32 s0, 0, 0
	v_writelane_b32 v254, s0, 31
	v_writelane_b32 v254, s22, 32
	s_add_i32 s0, s22, 0xfffff800
	v_writelane_b32 v254, s0, 33
	s_add_i32 s0, s18, 0xfffee000
	v_writelane_b32 v254, s0, 34
	v_readlane_b32 s0, v251, 4
	v_readlane_b32 s2, v251, 6
	v_readlane_b32 s1, v251, 5
	v_readlane_b32 s3, v251, 7
	s_add_u32 s0, s2, 0x3810
	v_writelane_b32 v251, s81, 57
	v_writelane_b32 v254, s0, 35
	s_addc_u32 s0, s3, 0
	v_writelane_b32 v251, s67, 56
	v_writelane_b32 v254, s0, 36
	s_add_i32 s2, 0, 0x18400
	v_writelane_b32 v251, s58, 61
	s_movk_i32 s0, 0x5600
	s_mov_b32 s1, 0x15800
	v_writelane_b32 v254, s2, 37
	v_mov_b32_e32 v231, 0x49742401
	v_mov_b64_e32 v[184:185], 0x400
	v_mov_b64_e32 v[186:187], 0x3ff
	v_mov_b64_e32 v[192:193], 0x1580
	v_mov_b64_e32 v[194:195], 0x157f
	s_mov_b32 s44, s77
	v_writelane_b32 v252, s57, 8
	v_writelane_b32 v251, s59, 62
	s_branch .LBB0_684

.LBB0_868:
	s_or_b64 exec, exec, s[2:3]
	s_waitcnt lgkmcnt(0)
	v_readlane_b32 s2, v252, 31
	s_add_i32 s7, s7, s2
	v_readlane_b32 s2, v254, 19
	s_add_i32 s6, s6, s2
	s_cmpk_lt_i32 s7, 0x4000
	s_cbranch_scc0 .LBB0_917

.LBB0_1043:
	s_and_b64 vcc, exec, s[2:3]
	v_readlane_b32 s79, v254, 32
	s_add_i32 s79, s79, 0x1800
	s_cbranch_vccnz .LBB0_1338
	v_readlane_b32 s2, v254, 49
	v_readlane_b32 s3, v254, 50
	s_add_u32 s26, s2, 0x8b200000
	s_addc_u32 s27, s3, 0
	s_add_u32 s4, s2, 0x8a400000
	s_addc_u32 s5, s3, 0
	v_writelane_b32 v254, s4, 52
	s_mov_b32 s97, 0
	s_nop 0
	v_writelane_b32 v254, s5, 53
	s_add_u32 s4, s2, 0x8b400000
	s_addc_u32 s5, s3, 0
	v_writelane_b32 v254, s4, 54
	s_nop 1
	v_writelane_b32 v254, s5, 55
	s_add_u32 s4, s2, 0x93400000
	v_writelane_b32 v254, s4, 56
	s_addc_u32 s4, s3, 0
	v_writelane_b32 v254, s4, 57
	s_add_u32 s4, s2, 0x8800000
	s_addc_u32 s5, s3, 0
	v_writelane_b32 v254, s4, 58
	s_nop 1
	v_writelane_b32 v254, s5, 59
	s_add_u32 s4, s2, 0x7000000
	s_addc_u32 s5, s3, 0
	v_writelane_b32 v254, s4, 60
	s_nop 1
	v_writelane_b32 v254, s5, 61
	s_add_u32 s4, s2, 0x4300000
	s_addc_u32 s5, s3, 0
	v_writelane_b32 v254, s4, 62
	s_nop 1
	v_writelane_b32 v254, s5, 63
	s_add_u32 s4, s2, 0x13800000
	s_addc_u32 s5, s3, 0
	v_writelane_b32 v250, s4, 0
	s_add_u32 s2, s2, 0x8b206000
	s_addc_u32 s3, s3, 0
	v_writelane_b32 v250, s5, 1
	v_writelane_b32 v250, s2, 2
	v_readlane_b32 s79, v254, 32
	s_add_i32 s79, s79, 0x1800
	s_nop 0
	v_writelane_b32 v250, s3, 3
	v_writelane_b32 v250, s26, 4
	v_writelane_b32 v250, s27, 5

.LBB0_1802:
	s_or_b64 exec, exec, s[2:3]
	s_waitcnt lgkmcnt(0)
	s_add_i32 s6, s6, 0xe000
	v_add_u32_e32 v80, 0xe000, v80
	v_add_u32_e32 v81, 0xe000, v81
	s_cmpk_lt_i32 s7, 0x3480
	s_mov_b32 s9, s7
	s_cbranch_scc0 .LBB0_1867
